# state update split into a V half (issued under the forward-substitution chain, operands packed over all lane groups) and an SA half; BF/VB operands dropped
# speedup vs baseline: 1.0160x; 1.0099x over previous
.Lmy_f_main:
	s_cmpk_ge_u32 s62, 0x100
	s_cbranch_scc1 .Lmy_f_hlp
	s_cmp_lg_u32 s65, 0
	s_cbranch_scc1 .Lmy_ck_nz
	v_mov_b32_e32 v208, 0
	v_mov_b32_e32 v209, 0
	v_mov_b32_e32 v210, 0
	v_mov_b32_e32 v211, 0
	v_mov_b32_e32 v212, 0
	v_mov_b32_e32 v213, 0
	v_mov_b32_e32 v214, 0
	v_mov_b32_e32 v215, 0
	v_mov_b32_e32 v216, 0
	v_mov_b32_e32 v217, 0
	v_mov_b32_e32 v218, 0
	v_mov_b32_e32 v219, 0
	v_mov_b32_e32 v220, 0
	v_mov_b32_e32 v221, 0
	v_mov_b32_e32 v222, 0
	v_mov_b32_e32 v223, 0
	v_xor_b32_e32 v1, v224, v234
	v_lshlrev_b32_e32 v1, 4, v1
	v_lshlrev_b32_e32 v2, 4, v234
	v_add_u32_e32 v2, 0x2000, v2
	v_mov_b32_e32 v72, 0x2600
	v_mov_b32_e32 v73, 0x2500
	v_mov_b32_e32 v74, 0x2510
	v_mov_b32_e32 v75, 0x2590
	v_cmp_eq_u32_e64 s[96:97], 0, v234
	v_and_b32_e32 v76, 1, v234
	v_lshrrev_b32_e32 v77, 1, v234
	v_cndmask_b32_e64 v3, v72, v73, s[96:97]
	v_cmp_eq_u32_e64 s[96:97], 1, v234
	v_and_b32_e32 v78, 1, v234
	v_add_u32_e32 v79, 2, v77
	v_cndmask_b32_e64 v4, v72, v74, s[96:97]
	v_cndmask_b32_e64 v5, v72, v75, s[96:97]
	v_lshlrev_b32_e32 v76, 10, v76
	v_lshl_add_u32 v76, v233, 2, v76
	v_add_u32_e32 v8, s62, v76
	v_lshlrev_b32_e32 v76, 9, v234
	v_lshl_add_u32 v76, v233, 2, v76
	v_add_u32_e32 v9, s62, v76
	v_lshl_add_u32 v6, v79, 4, v233
	v_xor_b32_e32 v6, v6, v79
	v_lshlrev_b32_e32 v6, 4, v6
	v_lshl_add_u32 v6, v78, 3, v6
	v_add_u32_e32 v6, 0x2100, v6
	v_lshl_add_u32 v7, v78, 4, v233
	v_xor_b32_e32 v7, v7, v78
	v_lshlrev_b32_e32 v7, 4, v7
	v_lshl_add_u32 v7, v77, 3, v7
	v_add_u32_e32 v7, 0x2100, v7
	v_lshlrev_b32_e32 v0, 4, v233
	v_lshl_add_u32 v0, v78, 8, v0
	v_lshl_add_u32 v0, v77, 3, v0
	v_add_u32_e32 v0, 0x1000, v0
	v_lshlrev_b32_e32 v10, 4, v233
	v_lshl_add_u32 v10, v79, 8, v10
	v_lshl_add_u32 v10, v78, 3, v10
	v_add_u32_e32 v10, 0x1000, v10
	v_add_u32_e32 v232, 48, v224
	v_and_b32_e32 v232, 63, v232
	v_lshlrev_b32_e32 v232, 2, v232
.Lmy_ck_nz:
	s_mov_b32 s100, 0xe000
	s_cmp_eq_u32 s23, 0
	s_cselect_b32 s100, 0x1c000, s100
	s_mov_b32 s101, 0x12e00
	s_cselect_b32 s101, 0x22100, s101
	s_lshl_b32 s96, s23, 13
	s_add_i32 s97, s96, 0x18000
	s_add_i32 s96, s96, 0xa000
	v_add_u32_e32 v225, s100, v1
	v_add_u32_e32 v236, s100, v0
	v_add_u32_e32 v34, s100, v10
	v_add_u32_e32 v226, s100, v2
	v_add_u32_e32 v227, s100, v3
	v_add_u32_e32 v228, s100, v4
	v_add_u32_e32 v229, s100, v5
	v_add_u32_e32 v237, s100, v6
	v_add_u32_e32 v238, s100, v7
	v_add_u32_e32 v230, s96, v8
	v_add_u32_e32 v239, s96, v9
	v_add_u32_e32 v231, s97, v8
	v_add_u32_e32 v26, s101, v1
	v_add_u32_e32 v27, s101, v0
	v_add_u32_e32 v35, s101, v10
	v_add_u32_e32 v28, s101, v2
	v_add_u32_e32 v29, s101, v3
	v_add_u32_e32 v30, s101, v4
	v_add_u32_e32 v31, s101, v5
	v_add_u32_e32 v32, s101, v6
	v_add_u32_e32 v33, s101, v7
	ds_read_b64 v[80:81], v237
	ds_read_b64 v[82:83], v238
	ds_read_b32 v36, v239
	ds_read_b32 v37, v239 offset:256
	ds_read_b128 v[88:91], v225
	ds_read_b128 v[92:95], v225 offset:1024
	ds_read_b128 v[96:99], v225 offset:2048
	ds_read_b128 v[100:103], v225 offset:3072
	ds_read_b32 v104, v227 offset:4
	ds_read_b32 v105, v227 offset:76
	ds_read_b64 v[106:107], v227 offset:8
	ds_read_b64 v[108:109], v227 offset:40
	ds_read_b32 v126, v229 offset:4
	ds_read_b32 v127, v229 offset:76
	ds_read_b64 v[128:129], v229 offset:8
	ds_read_b64 v[130:131], v229 offset:40
	ds_read_b64 v[110:111], v228
	ds_read_b64 v[112:113], v228 offset:32
	ds_read_b64 v[114:115], v228 offset:64
	ds_read_b64 v[116:117], v228 offset:96
	ds_read_b64 v[118:119], v228 offset:8
	ds_read_b64 v[120:121], v228 offset:40
	ds_read_b64 v[122:123], v228 offset:72
	ds_read_b64 v[124:125], v228 offset:104
	s_waitcnt lgkmcnt(15)
	v_mfma_f32_16x16x4_f32 v[240:243], v80, v36, 0
	v_mfma_f32_16x16x4_f32 v[240:243], v81, v37, v[240:243]
	v_mfma_f32_16x16x4_f32 v[240:243], v88, v208, v[240:243]
	ds_read_b64 v[186:187], v34
	ds_read_b64 v[190:191], v34 offset:1024
	v_mfma_f32_16x16x4_f32 v[244:247], v89, v209, 0
	ds_read_b64 v[194:195], v34 offset:2048
	ds_read_b64 v[198:199], v34 offset:3072
	v_mfma_f32_16x16x4_f32 v[240:243], v90, v210, v[240:243]
	ds_read_b64 v[184:185], v236
	ds_read_b64 v[188:189], v236 offset:1024
	ds_read_b64 v[132:133], v237 offset:9984
	ds_read_b64 v[134:135], v238 offset:9984
	v_mfma_f32_16x16x4_f32 v[244:247], v91, v211, v[244:247]
	ds_read_b64 v[192:193], v236 offset:2048
	ds_read_b64 v[196:197], v236 offset:3072
	ds_read_b32 v38, v239 offset:2048
	ds_read_b32 v39, v239 offset:2304
	v_mfma_f32_16x16x4_f32 v[240:243], v92, v212, v[240:243]
	ds_read_b128 v[140:143], v225 offset:9984
	ds_read_b128 v[144:147], v225 offset:11008
	v_mfma_f32_16x16x4_f32 v[244:247], v93, v213, v[244:247]
	ds_read_b128 v[148:151], v225 offset:12032
	ds_read_b128 v[152:155], v225 offset:13056
	v_mfma_f32_16x16x4_f32 v[240:243], v94, v214, v[240:243]
	ds_read_b32 v156, v227 offset:9988
	ds_read_b32 v157, v227 offset:10060
	v_mfma_f32_16x16x4_f32 v[244:247], v95, v215, v[244:247]
	ds_read_b64 v[158:159], v227 offset:9992
	ds_read_b64 v[160:161], v227 offset:10024
	v_mfma_f32_16x16x4_f32 v[240:243], v96, v216, v[240:243]
	ds_read_b32 v178, v229 offset:9988
	ds_read_b32 v179, v229 offset:10060
	v_mfma_f32_16x16x4_f32 v[244:247], v97, v217, v[244:247]
	ds_read_b64 v[180:181], v229 offset:9992
	ds_read_b64 v[182:183], v229 offset:10024
	v_mfma_f32_16x16x4_f32 v[240:243], v98, v218, v[240:243]
	ds_read_b64 v[162:163], v228 offset:9984
	ds_read_b64 v[164:165], v228 offset:10016
	v_mfma_f32_16x16x4_f32 v[244:247], v99, v219, v[244:247]
	ds_read_b64 v[166:167], v228 offset:10048
	ds_read_b64 v[168:169], v228 offset:10080
	v_mfma_f32_16x16x4_f32 v[240:243], v100, v220, v[240:243]
	ds_read_b64 v[170:171], v228 offset:9992
	ds_read_b64 v[172:173], v228 offset:10024
	v_mfma_f32_16x16x4_f32 v[244:247], v101, v221, v[244:247]
	ds_read_b64 v[174:175], v228 offset:10056
	ds_read_b64 v[176:177], v228 offset:10088
	v_mfma_f32_16x16x4_f32 v[240:243], v102, v222, v[240:243]
	v_mfma_f32_16x16x4_f32 v[244:247], v103, v223, v[244:247]
	s_waitcnt lgkmcnt(15)
	v_mfma_f32_16x16x4_f32 v[208:211], v186, v36, v[208:211]
	s_nop 2
	v_pk_add_f32 v[240:241], v[240:241], v[244:245]
	v_pk_add_f32 v[242:243], v[242:243], v[246:247]
	v_fmac_f32_e32 v241, v104, v240
	v_mfma_f32_16x16x4_f32 v[212:215], v190, v36, v[212:215]
	v_pk_fma_f32 v[242:243], v[106:107], v[240:241], v[242:243] op_sel:[0,0,0] op_sel_hi:[1,0,1]
	v_pk_fma_f32 v[242:243], v[108:109], v[240:241], v[242:243] op_sel:[0,1,0] op_sel_hi:[1,1,1]
	v_fmac_f32_e32 v243, v105, v242
	v_mfma_f32_16x16x4_f32 v[216:219], v194, v36, v[216:219]
	ds_bpermute_b32 v204, v232, v240
	ds_bpermute_b32 v205, v232, v241
	ds_bpermute_b32 v206, v232, v242
	v_mfma_f32_16x16x4_f32 v[72:75], v132, v38, 0
	ds_bpermute_b32 v207, v232, v243
	ds_read_b128 v[88:91], v226
	ds_read_b128 v[92:95], v226 offset:64
	v_mfma_f32_16x16x4_f32 v[72:75], v133, v39, v[72:75]
	ds_read_b128 v[96:99], v226 offset:128
	ds_read_b128 v[100:103], v226 offset:192
	s_waitcnt lgkmcnt(6)
	v_pk_fma_f32 v[240:241], v[110:111], v[204:205], v[240:241] op_sel:[0,0,0] op_sel_hi:[1,0,1]
	v_mfma_f32_16x16x4_f32 v[220:223], v198, v36, v[220:223]
	v_pk_fma_f32 v[240:241], v[112:113], v[204:205], v[240:241] op_sel:[0,1,0] op_sel_hi:[1,1,1]
	s_waitcnt lgkmcnt(4)
	v_pk_fma_f32 v[240:241], v[114:115], v[206:207], v[240:241] op_sel:[0,0,0] op_sel_hi:[1,0,1]
	v_pk_fma_f32 v[240:241], v[116:117], v[206:207], v[240:241] op_sel:[0,1,0] op_sel_hi:[1,1,1]
	v_mfma_f32_16x16x4_f32 v[208:211], v187, v37, v[208:211]
	v_pk_fma_f32 v[242:243], v[118:119], v[204:205], v[242:243] op_sel:[0,0,0] op_sel_hi:[1,0,1]
	v_pk_fma_f32 v[242:243], v[120:121], v[204:205], v[242:243] op_sel:[0,1,0] op_sel_hi:[1,1,1]
	v_pk_fma_f32 v[242:243], v[122:123], v[206:207], v[242:243] op_sel:[0,0,0] op_sel_hi:[1,0,1]
	v_mfma_f32_16x16x4_f32 v[212:215], v191, v37, v[212:215]
	v_pk_fma_f32 v[242:243], v[124:125], v[206:207], v[242:243] op_sel:[0,1,0] op_sel_hi:[1,1,1]
	v_fmac_f32_e32 v241, v126, v240
	v_pk_fma_f32 v[242:243], v[128:129], v[240:241], v[242:243] op_sel:[0,0,0] op_sel_hi:[1,0,1]
	v_mfma_f32_16x16x4_f32 v[216:219], v195, v37, v[216:219]
	v_pk_fma_f32 v[242:243], v[130:131], v[240:241], v[242:243] op_sel:[0,1,0] op_sel_hi:[1,1,1]
	v_fmac_f32_e32 v243, v127, v242
	v_mov_b32_e32 v252, v240
	v_mfma_f32_16x16x4_f32 v[220:223], v199, v37, v[220:223]
	v_mov_b32_e32 v253, v241
	v_mov_b32_e32 v254, v242
	v_mov_b32_e32 v255, v243
	s_nop 0
	v_permlane32_swap_b32_e32 v252, v254
	v_permlane32_swap_b32_e32 v253, v255
	s_nop 0
	v_mfma_f32_16x16x4_f32 v[208:211], v184, v252, v[208:211]
	v_mfma_f32_16x16x4_f32 v[212:215], v188, v252, v[212:215]
	v_mfma_f32_16x16x4_f32 v[216:219], v192, v252, v[216:219]
	v_mfma_f32_16x16x4_f32 v[220:223], v196, v252, v[220:223]
	v_mfma_f32_16x16x4_f32 v[208:211], v185, v253, v[208:211]
	v_mfma_f32_16x16x4_f32 v[212:215], v189, v253, v[212:215]
	v_mfma_f32_16x16x4_f32 v[216:219], v193, v253, v[216:219]
	v_mfma_f32_16x16x4_f32 v[220:223], v197, v253, v[220:223]
	v_mfma_f32_16x16x4_f32 v[248:251], v82, v252, v[240:243]
	v_mfma_f32_16x16x4_f32 v[248:251], v83, v253, v[248:251]
	s_waitcnt lgkmcnt(3)
	v_pk_mul_f32 v[208:209], v[208:209], v[88:89]
	v_pk_mul_f32 v[210:211], v[210:211], v[90:91]
	s_nop 0
	v_mfma_f32_16x16x4_f32 v[72:75], v140, v208, v[72:75]
	s_waitcnt lgkmcnt(2)
	v_pk_mul_f32 v[212:213], v[212:213], v[92:93]
	v_mfma_f32_16x16x4_f32 v[244:247], v141, v209, 0
	v_pk_mul_f32 v[214:215], v[214:215], v[94:95]
	v_mfma_f32_16x16x4_f32 v[72:75], v142, v210, v[72:75]
	s_waitcnt lgkmcnt(1)
	v_pk_mul_f32 v[216:217], v[216:217], v[96:97]
	v_mfma_f32_16x16x4_f32 v[244:247], v143, v211, v[244:247]
	v_pk_mul_f32 v[218:219], v[218:219], v[98:99]
	v_mfma_f32_16x16x4_f32 v[72:75], v144, v212, v[72:75]
	s_waitcnt lgkmcnt(0)
	v_pk_mul_f32 v[220:221], v[220:221], v[100:101]
	v_mfma_f32_16x16x4_f32 v[244:247], v145, v213, v[244:247]
	v_pk_mul_f32 v[222:223], v[222:223], v[102:103]
	v_mfma_f32_16x16x4_f32 v[72:75], v146, v214, v[72:75]
	s_mov_b64 exec, s[98:99]
	ds_write_b32 v231, v248
	ds_write_b32 v231, v249 offset:256
	ds_write_b32 v231, v250 offset:512
	ds_write_b32 v231, v251 offset:768
	s_mov_b64 exec, -1
	ds_read_b64 v[186:187], v34 offset:9984
	ds_read_b64 v[190:191], v34 offset:11008
	v_mfma_f32_16x16x4_f32 v[244:247], v147, v215, v[244:247]
	ds_read_b64 v[194:195], v34 offset:12032
	ds_read_b64 v[198:199], v34 offset:13056
	v_mfma_f32_16x16x4_f32 v[72:75], v148, v216, v[72:75]
	ds_read_b64 v[184:185], v236 offset:9984
	ds_read_b64 v[188:189], v236 offset:11008
	ds_read_b64 v[80:81], v32
	ds_read_b64 v[82:83], v33
	ds_read_b32 v36, v239 offset:4096
	v_mfma_f32_16x16x4_f32 v[244:247], v149, v217, v[244:247]
	ds_read_b64 v[192:193], v236 offset:12032
	ds_read_b64 v[196:197], v236 offset:13056
	ds_read_b32 v37, v239 offset:4352
	ds_read_b128 v[88:91], v26
	ds_read_b128 v[92:95], v26 offset:1024
	v_mfma_f32_16x16x4_f32 v[72:75], v150, v218, v[72:75]
	ds_read_b128 v[96:99], v26 offset:2048
	ds_read_b128 v[100:103], v26 offset:3072
	ds_read_b32 v104, v29 offset:4
	v_mfma_f32_16x16x4_f32 v[244:247], v151, v219, v[244:247]
	ds_read_b32 v105, v29 offset:76
	ds_read_b64 v[106:107], v29 offset:8
	ds_read_b64 v[108:109], v29 offset:40
	v_mfma_f32_16x16x4_f32 v[72:75], v152, v220, v[72:75]
	ds_read_b32 v126, v31 offset:4
	ds_read_b32 v127, v31 offset:76
	ds_read_b64 v[128:129], v31 offset:8
	v_mfma_f32_16x16x4_f32 v[244:247], v153, v221, v[244:247]
	ds_read_b64 v[130:131], v31 offset:40
	ds_read_b64 v[110:111], v30
	ds_read_b64 v[112:113], v30 offset:32
	v_mfma_f32_16x16x4_f32 v[72:75], v154, v222, v[72:75]
	ds_read_b64 v[114:115], v30 offset:64
	ds_read_b64 v[116:117], v30 offset:96
	ds_read_b64 v[118:119], v30 offset:8
	v_mfma_f32_16x16x4_f32 v[244:247], v155, v223, v[244:247]
	ds_read_b64 v[120:121], v30 offset:40
	ds_read_b64 v[122:123], v30 offset:72
	ds_read_b64 v[124:125], v30 offset:104
	s_waitcnt lgkmcnt(15)
	v_mfma_f32_16x16x4_f32 v[208:211], v186, v38, v[208:211]
	s_nop 5
	v_pk_add_f32 v[72:73], v[72:73], v[244:245]
	v_pk_add_f32 v[74:75], v[74:75], v[246:247]
	v_fmac_f32_e32 v73, v156, v72
	v_mfma_f32_16x16x4_f32 v[212:215], v190, v38, v[212:215]
	v_pk_fma_f32 v[74:75], v[158:159], v[72:73], v[74:75] op_sel:[0,0,0] op_sel_hi:[1,0,1]
	v_pk_fma_f32 v[74:75], v[160:161], v[72:73], v[74:75] op_sel:[0,1,0] op_sel_hi:[1,1,1]
	v_fmac_f32_e32 v75, v157, v74
	v_mfma_f32_16x16x4_f32 v[216:219], v194, v38, v[216:219]
	ds_bpermute_b32 v204, v232, v72
	ds_bpermute_b32 v205, v232, v73
	ds_bpermute_b32 v206, v232, v74
	v_mfma_f32_16x16x4_f32 v[240:243], v80, v36, 0
	ds_bpermute_b32 v207, v232, v75
	ds_read_b128 v[140:143], v226 offset:9984
	ds_read_b128 v[144:147], v226 offset:10048
	v_mfma_f32_16x16x4_f32 v[240:243], v81, v37, v[240:243]
	ds_read_b128 v[148:151], v226 offset:10112
	ds_read_b128 v[152:155], v226 offset:10176
	s_waitcnt lgkmcnt(6)
	v_pk_fma_f32 v[72:73], v[162:163], v[204:205], v[72:73] op_sel:[0,0,0] op_sel_hi:[1,0,1]
	v_mfma_f32_16x16x4_f32 v[220:223], v198, v38, v[220:223]
	v_pk_fma_f32 v[72:73], v[164:165], v[204:205], v[72:73] op_sel:[0,1,0] op_sel_hi:[1,1,1]
	s_waitcnt lgkmcnt(4)
	v_pk_fma_f32 v[72:73], v[166:167], v[206:207], v[72:73] op_sel:[0,0,0] op_sel_hi:[1,0,1]
	v_pk_fma_f32 v[72:73], v[168:169], v[206:207], v[72:73] op_sel:[0,1,0] op_sel_hi:[1,1,1]
	v_mfma_f32_16x16x4_f32 v[208:211], v187, v39, v[208:211]
	v_pk_fma_f32 v[74:75], v[170:171], v[204:205], v[74:75] op_sel:[0,0,0] op_sel_hi:[1,0,1]
	v_pk_fma_f32 v[74:75], v[172:173], v[204:205], v[74:75] op_sel:[0,1,0] op_sel_hi:[1,1,1]
	v_pk_fma_f32 v[74:75], v[174:175], v[206:207], v[74:75] op_sel:[0,0,0] op_sel_hi:[1,0,1]
	v_mfma_f32_16x16x4_f32 v[212:215], v191, v39, v[212:215]
	v_pk_fma_f32 v[74:75], v[176:177], v[206:207], v[74:75] op_sel:[0,1,0] op_sel_hi:[1,1,1]
	v_fmac_f32_e32 v73, v178, v72
	v_pk_fma_f32 v[74:75], v[180:181], v[72:73], v[74:75] op_sel:[0,0,0] op_sel_hi:[1,0,1]
	v_mfma_f32_16x16x4_f32 v[216:219], v195, v39, v[216:219]
	v_pk_fma_f32 v[74:75], v[182:183], v[72:73], v[74:75] op_sel:[0,1,0] op_sel_hi:[1,1,1]
	v_fmac_f32_e32 v75, v179, v74
	v_mov_b32_e32 v252, v72
	v_mfma_f32_16x16x4_f32 v[220:223], v199, v39, v[220:223]
	v_mov_b32_e32 v253, v73
	v_mov_b32_e32 v254, v74
	v_mov_b32_e32 v255, v75
	s_nop 0
	v_permlane32_swap_b32_e32 v252, v254
	v_permlane32_swap_b32_e32 v253, v255
	s_nop 0
	v_mfma_f32_16x16x4_f32 v[208:211], v184, v252, v[208:211]
	v_mfma_f32_16x16x4_f32 v[212:215], v188, v252, v[212:215]
	v_mfma_f32_16x16x4_f32 v[216:219], v192, v252, v[216:219]
	v_mfma_f32_16x16x4_f32 v[220:223], v196, v252, v[220:223]
	v_mfma_f32_16x16x4_f32 v[208:211], v185, v253, v[208:211]
	v_mfma_f32_16x16x4_f32 v[212:215], v189, v253, v[212:215]
	v_mfma_f32_16x16x4_f32 v[216:219], v193, v253, v[216:219]
	v_mfma_f32_16x16x4_f32 v[220:223], v197, v253, v[220:223]
	v_mfma_f32_16x16x4_f32 v[248:251], v134, v252, v[72:75]
	v_mfma_f32_16x16x4_f32 v[248:251], v135, v253, v[248:251]
	s_waitcnt lgkmcnt(3)
	v_pk_mul_f32 v[208:209], v[208:209], v[140:141]
	v_pk_mul_f32 v[210:211], v[210:211], v[142:143]
	s_nop 0
	v_mfma_f32_16x16x4_f32 v[240:243], v88, v208, v[240:243]
	s_waitcnt lgkmcnt(2)
	v_pk_mul_f32 v[212:213], v[212:213], v[144:145]
	v_mfma_f32_16x16x4_f32 v[244:247], v89, v209, 0
	v_pk_mul_f32 v[214:215], v[214:215], v[146:147]
	v_mfma_f32_16x16x4_f32 v[240:243], v90, v210, v[240:243]
	s_waitcnt lgkmcnt(1)
	v_pk_mul_f32 v[216:217], v[216:217], v[148:149]
	v_mfma_f32_16x16x4_f32 v[244:247], v91, v211, v[244:247]
	v_pk_mul_f32 v[218:219], v[218:219], v[150:151]
	v_mfma_f32_16x16x4_f32 v[240:243], v92, v212, v[240:243]
	s_waitcnt lgkmcnt(0)
	v_pk_mul_f32 v[220:221], v[220:221], v[152:153]
	v_mfma_f32_16x16x4_f32 v[244:247], v93, v213, v[244:247]
	v_pk_mul_f32 v[222:223], v[222:223], v[154:155]
	v_mfma_f32_16x16x4_f32 v[240:243], v94, v214, v[240:243]
	s_mov_b64 exec, s[98:99]
	ds_write_b32 v231, v248 offset:2048
	ds_write_b32 v231, v249 offset:2304
	ds_write_b32 v231, v250 offset:2560
	ds_write_b32 v231, v251 offset:2816
	s_mov_b64 exec, -1
	ds_read_b64 v[186:187], v35
	ds_read_b64 v[190:191], v35 offset:1024
	v_mfma_f32_16x16x4_f32 v[244:247], v95, v215, v[244:247]
	ds_read_b64 v[194:195], v35 offset:2048
	ds_read_b64 v[198:199], v35 offset:3072
	v_mfma_f32_16x16x4_f32 v[240:243], v96, v216, v[240:243]
	ds_read_b64 v[184:185], v27
	ds_read_b64 v[188:189], v27 offset:1024
	ds_read_b64 v[132:133], v32 offset:9984
	ds_read_b64 v[134:135], v33 offset:9984
	ds_read_b32 v38, v239 offset:6144
	v_mfma_f32_16x16x4_f32 v[244:247], v97, v217, v[244:247]
	ds_read_b64 v[192:193], v27 offset:2048
	ds_read_b64 v[196:197], v27 offset:3072
	ds_read_b32 v39, v239 offset:6400
	ds_read_b128 v[140:143], v26 offset:9984
	ds_read_b128 v[144:147], v26 offset:11008
	v_mfma_f32_16x16x4_f32 v[240:243], v98, v218, v[240:243]
	ds_read_b128 v[148:151], v26 offset:12032
	ds_read_b128 v[152:155], v26 offset:13056
	ds_read_b32 v156, v29 offset:9988
	v_mfma_f32_16x16x4_f32 v[244:247], v99, v219, v[244:247]
	ds_read_b32 v157, v29 offset:10060
	ds_read_b64 v[158:159], v29 offset:9992
	ds_read_b64 v[160:161], v29 offset:10024
	v_mfma_f32_16x16x4_f32 v[240:243], v100, v220, v[240:243]
	ds_read_b32 v178, v31 offset:9988
	ds_read_b32 v179, v31 offset:10060
	ds_read_b64 v[180:181], v31 offset:9992
	v_mfma_f32_16x16x4_f32 v[244:247], v101, v221, v[244:247]
	ds_read_b64 v[182:183], v31 offset:10024
	ds_read_b64 v[162:163], v30 offset:9984
	ds_read_b64 v[164:165], v30 offset:10016
	v_mfma_f32_16x16x4_f32 v[240:243], v102, v222, v[240:243]
	ds_read_b64 v[166:167], v30 offset:10048
	ds_read_b64 v[168:169], v30 offset:10080
	ds_read_b64 v[170:171], v30 offset:9992
	v_mfma_f32_16x16x4_f32 v[244:247], v103, v223, v[244:247]
	ds_read_b64 v[172:173], v30 offset:10024
	ds_read_b64 v[174:175], v30 offset:10056
	ds_read_b64 v[176:177], v30 offset:10088
	s_waitcnt lgkmcnt(15)
	v_mfma_f32_16x16x4_f32 v[208:211], v186, v36, v[208:211]
	s_nop 5
	v_pk_add_f32 v[240:241], v[240:241], v[244:245]
	v_pk_add_f32 v[242:243], v[242:243], v[246:247]
	v_fmac_f32_e32 v241, v104, v240
	v_mfma_f32_16x16x4_f32 v[212:215], v190, v36, v[212:215]
	v_pk_fma_f32 v[242:243], v[106:107], v[240:241], v[242:243] op_sel:[0,0,0] op_sel_hi:[1,0,1]
	v_pk_fma_f32 v[242:243], v[108:109], v[240:241], v[242:243] op_sel:[0,1,0] op_sel_hi:[1,1,1]
	v_fmac_f32_e32 v243, v105, v242
	v_mfma_f32_16x16x4_f32 v[216:219], v194, v36, v[216:219]
	ds_bpermute_b32 v204, v232, v240
	ds_bpermute_b32 v205, v232, v241
	ds_bpermute_b32 v206, v232, v242
	v_mfma_f32_16x16x4_f32 v[72:75], v132, v38, 0
	ds_bpermute_b32 v207, v232, v243
	ds_read_b128 v[88:91], v28
	ds_read_b128 v[92:95], v28 offset:64
	v_mfma_f32_16x16x4_f32 v[72:75], v133, v39, v[72:75]
	ds_read_b128 v[96:99], v28 offset:128
	ds_read_b128 v[100:103], v28 offset:192
	s_waitcnt lgkmcnt(6)
	v_pk_fma_f32 v[240:241], v[110:111], v[204:205], v[240:241] op_sel:[0,0,0] op_sel_hi:[1,0,1]
	v_mfma_f32_16x16x4_f32 v[220:223], v198, v36, v[220:223]
	v_pk_fma_f32 v[240:241], v[112:113], v[204:205], v[240:241] op_sel:[0,1,0] op_sel_hi:[1,1,1]
	s_waitcnt lgkmcnt(4)
	v_pk_fma_f32 v[240:241], v[114:115], v[206:207], v[240:241] op_sel:[0,0,0] op_sel_hi:[1,0,1]
	v_pk_fma_f32 v[240:241], v[116:117], v[206:207], v[240:241] op_sel:[0,1,0] op_sel_hi:[1,1,1]
	v_mfma_f32_16x16x4_f32 v[208:211], v187, v37, v[208:211]
	v_pk_fma_f32 v[242:243], v[118:119], v[204:205], v[242:243] op_sel:[0,0,0] op_sel_hi:[1,0,1]
	v_pk_fma_f32 v[242:243], v[120:121], v[204:205], v[242:243] op_sel:[0,1,0] op_sel_hi:[1,1,1]
	v_pk_fma_f32 v[242:243], v[122:123], v[206:207], v[242:243] op_sel:[0,0,0] op_sel_hi:[1,0,1]
	v_mfma_f32_16x16x4_f32 v[212:215], v191, v37, v[212:215]
	v_pk_fma_f32 v[242:243], v[124:125], v[206:207], v[242:243] op_sel:[0,1,0] op_sel_hi:[1,1,1]
	v_fmac_f32_e32 v241, v126, v240
	v_pk_fma_f32 v[242:243], v[128:129], v[240:241], v[242:243] op_sel:[0,0,0] op_sel_hi:[1,0,1]
	v_mfma_f32_16x16x4_f32 v[216:219], v195, v37, v[216:219]
	v_pk_fma_f32 v[242:243], v[130:131], v[240:241], v[242:243] op_sel:[0,1,0] op_sel_hi:[1,1,1]
	v_fmac_f32_e32 v243, v127, v242
	v_mov_b32_e32 v252, v240
	v_mfma_f32_16x16x4_f32 v[220:223], v199, v37, v[220:223]
	v_mov_b32_e32 v253, v241
	v_mov_b32_e32 v254, v242
	v_mov_b32_e32 v255, v243
	s_nop 0
	v_permlane32_swap_b32_e32 v252, v254
	v_permlane32_swap_b32_e32 v253, v255
	s_nop 0
	v_mfma_f32_16x16x4_f32 v[208:211], v184, v252, v[208:211]
	v_mfma_f32_16x16x4_f32 v[212:215], v188, v252, v[212:215]
	v_mfma_f32_16x16x4_f32 v[216:219], v192, v252, v[216:219]
	v_mfma_f32_16x16x4_f32 v[220:223], v196, v252, v[220:223]
	v_mfma_f32_16x16x4_f32 v[208:211], v185, v253, v[208:211]
	v_mfma_f32_16x16x4_f32 v[212:215], v189, v253, v[212:215]
	v_mfma_f32_16x16x4_f32 v[216:219], v193, v253, v[216:219]
	v_mfma_f32_16x16x4_f32 v[220:223], v197, v253, v[220:223]
	v_mfma_f32_16x16x4_f32 v[248:251], v82, v252, v[240:243]
	v_mfma_f32_16x16x4_f32 v[248:251], v83, v253, v[248:251]
	s_waitcnt lgkmcnt(3)
	v_pk_mul_f32 v[208:209], v[208:209], v[88:89]
	v_pk_mul_f32 v[210:211], v[210:211], v[90:91]
	s_nop 0
	v_mfma_f32_16x16x4_f32 v[72:75], v140, v208, v[72:75]
	s_waitcnt lgkmcnt(2)
	v_pk_mul_f32 v[212:213], v[212:213], v[92:93]
	v_mfma_f32_16x16x4_f32 v[244:247], v141, v209, 0
	v_pk_mul_f32 v[214:215], v[214:215], v[94:95]
	v_mfma_f32_16x16x4_f32 v[72:75], v142, v210, v[72:75]
	s_waitcnt lgkmcnt(1)
	v_pk_mul_f32 v[216:217], v[216:217], v[96:97]
	v_mfma_f32_16x16x4_f32 v[244:247], v143, v211, v[244:247]
	v_pk_mul_f32 v[218:219], v[218:219], v[98:99]
	v_mfma_f32_16x16x4_f32 v[72:75], v144, v212, v[72:75]
	s_waitcnt lgkmcnt(0)
	v_pk_mul_f32 v[220:221], v[220:221], v[100:101]
	v_mfma_f32_16x16x4_f32 v[244:247], v145, v213, v[244:247]
	v_pk_mul_f32 v[222:223], v[222:223], v[102:103]
	v_mfma_f32_16x16x4_f32 v[72:75], v146, v214, v[72:75]
	s_mov_b64 exec, s[98:99]
	ds_write_b32 v231, v248 offset:4096
	ds_write_b32 v231, v249 offset:4352
	ds_write_b32 v231, v250 offset:4608
	ds_write_b32 v231, v251 offset:4864
	s_mov_b64 exec, -1
	ds_read_b64 v[186:187], v35 offset:9984
	ds_read_b64 v[190:191], v35 offset:11008
	v_mfma_f32_16x16x4_f32 v[244:247], v147, v215, v[244:247]
	ds_read_b64 v[194:195], v35 offset:12032
	ds_read_b64 v[198:199], v35 offset:13056
	v_mfma_f32_16x16x4_f32 v[72:75], v148, v216, v[72:75]
	ds_read_b64 v[184:185], v27 offset:9984
	ds_read_b64 v[188:189], v27 offset:11008
	v_mfma_f32_16x16x4_f32 v[244:247], v149, v217, v[244:247]
	ds_read_b64 v[192:193], v27 offset:12032
	ds_read_b64 v[196:197], v27 offset:13056
	v_mfma_f32_16x16x4_f32 v[72:75], v150, v218, v[72:75]
	v_mfma_f32_16x16x4_f32 v[244:247], v151, v219, v[244:247]
	v_mfma_f32_16x16x4_f32 v[72:75], v152, v220, v[72:75]
	v_mfma_f32_16x16x4_f32 v[244:247], v153, v221, v[244:247]
	v_mfma_f32_16x16x4_f32 v[72:75], v154, v222, v[72:75]
	v_mfma_f32_16x16x4_f32 v[244:247], v155, v223, v[244:247]
	s_waitcnt lgkmcnt(7)
	v_mfma_f32_16x16x4_f32 v[208:211], v186, v38, v[208:211]
	s_nop 2
	v_pk_add_f32 v[72:73], v[72:73], v[244:245]
	v_pk_add_f32 v[74:75], v[74:75], v[246:247]
	v_fmac_f32_e32 v73, v156, v72
	s_waitcnt lgkmcnt(6)
	v_mfma_f32_16x16x4_f32 v[212:215], v190, v38, v[212:215]
	v_pk_fma_f32 v[74:75], v[158:159], v[72:73], v[74:75] op_sel:[0,0,0] op_sel_hi:[1,0,1]
	v_pk_fma_f32 v[74:75], v[160:161], v[72:73], v[74:75] op_sel:[0,1,0] op_sel_hi:[1,1,1]
	v_fmac_f32_e32 v75, v157, v74
	s_waitcnt lgkmcnt(5)
	v_mfma_f32_16x16x4_f32 v[216:219], v194, v38, v[216:219]
	ds_bpermute_b32 v204, v232, v72
	ds_bpermute_b32 v205, v232, v73
	ds_bpermute_b32 v206, v232, v74
	s_waitcnt lgkmcnt(7)
	v_mfma_f32_16x16x4_f32 v[220:223], v198, v38, v[220:223]
	ds_bpermute_b32 v207, v232, v75
	ds_read_b128 v[140:143], v28 offset:9984
	ds_read_b128 v[144:147], v28 offset:10048
	v_mfma_f32_16x16x4_f32 v[208:211], v187, v39, v[208:211]
	ds_read_b128 v[148:151], v28 offset:10112
	ds_read_b128 v[152:155], v28 offset:10176
	s_waitcnt lgkmcnt(6)
	v_pk_fma_f32 v[72:73], v[162:163], v[204:205], v[72:73] op_sel:[0,0,0] op_sel_hi:[1,0,1]
	v_mfma_f32_16x16x4_f32 v[212:215], v191, v39, v[212:215]
	v_pk_fma_f32 v[72:73], v[164:165], v[204:205], v[72:73] op_sel:[0,1,0] op_sel_hi:[1,1,1]
	s_waitcnt lgkmcnt(4)
	v_pk_fma_f32 v[72:73], v[166:167], v[206:207], v[72:73] op_sel:[0,0,0] op_sel_hi:[1,0,1]
	v_pk_fma_f32 v[72:73], v[168:169], v[206:207], v[72:73] op_sel:[0,1,0] op_sel_hi:[1,1,1]
	v_mfma_f32_16x16x4_f32 v[216:219], v195, v39, v[216:219]
	v_pk_fma_f32 v[74:75], v[170:171], v[204:205], v[74:75] op_sel:[0,0,0] op_sel_hi:[1,0,1]
	v_pk_fma_f32 v[74:75], v[172:173], v[204:205], v[74:75] op_sel:[0,1,0] op_sel_hi:[1,1,1]
	v_pk_fma_f32 v[74:75], v[174:175], v[206:207], v[74:75] op_sel:[0,0,0] op_sel_hi:[1,0,1]
	v_mfma_f32_16x16x4_f32 v[220:223], v199, v39, v[220:223]
	v_pk_fma_f32 v[74:75], v[176:177], v[206:207], v[74:75] op_sel:[0,1,0] op_sel_hi:[1,1,1]
	v_fmac_f32_e32 v73, v178, v72
	v_pk_fma_f32 v[74:75], v[180:181], v[72:73], v[74:75] op_sel:[0,0,0] op_sel_hi:[1,0,1]
	v_pk_fma_f32 v[74:75], v[182:183], v[72:73], v[74:75] op_sel:[0,1,0] op_sel_hi:[1,1,1]
	v_fmac_f32_e32 v75, v179, v74
	v_mov_b32_e32 v252, v72
	v_mov_b32_e32 v253, v73
	v_mov_b32_e32 v254, v74
	v_mov_b32_e32 v255, v75
	s_nop 0
	v_permlane32_swap_b32_e32 v252, v254
	v_permlane32_swap_b32_e32 v253, v255
	s_nop 0
	v_mfma_f32_16x16x4_f32 v[208:211], v184, v252, v[208:211]
	v_mfma_f32_16x16x4_f32 v[212:215], v188, v252, v[212:215]
	v_mfma_f32_16x16x4_f32 v[216:219], v192, v252, v[216:219]
	v_mfma_f32_16x16x4_f32 v[220:223], v196, v252, v[220:223]
	v_mfma_f32_16x16x4_f32 v[208:211], v185, v253, v[208:211]
	v_mfma_f32_16x16x4_f32 v[212:215], v189, v253, v[212:215]
	v_mfma_f32_16x16x4_f32 v[216:219], v193, v253, v[216:219]
	v_mfma_f32_16x16x4_f32 v[220:223], v197, v253, v[220:223]
	v_mfma_f32_16x16x4_f32 v[248:251], v134, v252, v[72:75]
	v_mfma_f32_16x16x4_f32 v[248:251], v135, v253, v[248:251]
	s_waitcnt lgkmcnt(3)
	v_pk_mul_f32 v[208:209], v[208:209], v[140:141]
	v_pk_mul_f32 v[210:211], v[210:211], v[142:143]
	s_waitcnt lgkmcnt(2)
	v_pk_mul_f32 v[212:213], v[212:213], v[144:145]
	v_pk_mul_f32 v[214:215], v[214:215], v[146:147]
	s_waitcnt lgkmcnt(1)
	v_pk_mul_f32 v[216:217], v[216:217], v[148:149]
	v_pk_mul_f32 v[218:219], v[218:219], v[150:151]
	s_waitcnt lgkmcnt(0)
	v_pk_mul_f32 v[220:221], v[220:221], v[152:153]
	v_pk_mul_f32 v[222:223], v[222:223], v[154:155]
	s_mov_b64 exec, s[98:99]
	s_nop 0
	ds_write_b32 v231, v248 offset:6144
	ds_write_b32 v231, v249 offset:6400
	ds_write_b32 v231, v250 offset:6656
	ds_write_b32 v231, v251 offset:6912
	s_mov_b64 exec, -1
	s_branch .LBB0_655

.Lmy_ck_drE_h:
	s_waitcnt lgkmcnt(0)
	s_bfe_u32 s96, s62, 0x20006
	s_and_b32 s97, s96, 1
	s_mul_i32 s97, s97, 0x2700
	s_mov_b32 s101, 0x1c000
	s_mov_b32 s100, 0x6100
	s_bitcmp0_b32 s65, 0
	s_cselect_b32 s101, 0xe000, s101
	s_cselect_b32 s100, 0x4e00, s100
	s_cmp_gt_u32 s96, 1
	s_cselect_b32 s100, s100, 0
	s_add_i32 s97, s97, s101
	s_add_i32 s97, s97, s100
	s_mov_b32 s96, s97
	v_and_b32_e32 v72, 3, v233
	v_lshrrev_b32_e32 v73, 2, v233
	v_lshlrev_b32_e32 v72, 2, v72
	v_lshl_add_u32 v72, v73, 8, v72
	v_lshl_add_u32 v72, v234, 6, v72
	s_add_i32 s97, s96, 0x1000
	v_add_u32_e32 v78, s97, v72
	v_xor_b32_e32 v79, v224, v234
	v_lshl_add_u32 v79, v79, 4, s96
	ds_read_b128 v[96:99], v79
	ds_read_b128 v[100:103], v79 offset:1024
	ds_read_b128 v[104:107], v79 offset:2048
	ds_read_b128 v[108:111], v79 offset:3072
	ds_read_b32 v80, v78
	ds_read_b32 v81, v78 offset:16
	ds_read_b32 v82, v78 offset:32
	ds_read_b32 v83, v78 offset:48
	ds_read_b32 v84, v78 offset:1024
	ds_read_b32 v85, v78 offset:1040
	ds_read_b32 v86, v78 offset:1056
	ds_read_b32 v87, v78 offset:1072
	ds_read_b32 v88, v78 offset:2048
	ds_read_b32 v89, v78 offset:2064
	ds_read_b32 v90, v78 offset:2080
	ds_read_b32 v91, v78 offset:2096
	ds_read_b32 v92, v78 offset:3072
	ds_read_b32 v93, v78 offset:3088
	ds_read_b32 v94, v78 offset:3104
	ds_read_b32 v95, v78 offset:3120
	v_lshl_add_u32 v74, v224, 2, s96
	ds_write_b32 v74, v235 offset:9728
	v_add_u32_e32 v75, -1, v233
	v_mov_b32_e32 v76, -1
	v_cndmask_b32_e64 v75, v76, v75, s[98:99]
	v_cmp_lt_u32_e64 s[100:101], 7, v233
	v_add_u32_e32 v76, -8, v233
	v_and_b32_e32 v77, 1, v234
	v_cndmask_b32_e64 v75, v75, v76, s[100:101]
	v_lshlrev_b32_e32 v77, 2, v77
	v_sub_u32_e32 v76, v75, v77
	v_lshlrev_b32_e32 v77, 2, v234
	v_sub_u32_e32 v77, v233, v77
	v_add_u32_e32 v77, -1, v77
	s_waitcnt lgkmcnt(15)
	v_mfma_f32_16x16x4_f32 v[244:247], v80, v96, 0
	v_mfma_f32_16x16x4_f32 v[240:243], v81, v97, 0
	s_waitcnt lgkmcnt(14)
	v_mfma_f32_16x16x4_f32 v[244:247], v82, v98, v[244:247]
	s_waitcnt lgkmcnt(13)
	v_mfma_f32_16x16x4_f32 v[240:243], v83, v99, v[240:243]
	s_waitcnt lgkmcnt(12)
	v_mfma_f32_16x16x4_f32 v[244:247], v84, v100, v[244:247]
	s_waitcnt lgkmcnt(11)
	v_mfma_f32_16x16x4_f32 v[240:243], v85, v101, v[240:243]
	s_waitcnt lgkmcnt(10)
	v_mfma_f32_16x16x4_f32 v[244:247], v86, v102, v[244:247]
	s_waitcnt lgkmcnt(9)
	v_mfma_f32_16x16x4_f32 v[240:243], v87, v103, v[240:243]
	s_waitcnt lgkmcnt(8)
	v_mfma_f32_16x16x4_f32 v[244:247], v88, v104, v[244:247]
	s_waitcnt lgkmcnt(7)
	v_mfma_f32_16x16x4_f32 v[240:243], v89, v105, v[240:243]
	s_waitcnt lgkmcnt(6)
	v_mfma_f32_16x16x4_f32 v[244:247], v90, v106, v[244:247]
	s_waitcnt lgkmcnt(5)
	v_mfma_f32_16x16x4_f32 v[240:243], v91, v107, v[240:243]
	s_waitcnt lgkmcnt(4)
	v_mfma_f32_16x16x4_f32 v[244:247], v92, v108, v[244:247]
	s_waitcnt lgkmcnt(3)
	v_mfma_f32_16x16x4_f32 v[240:243], v93, v109, v[240:243]
	s_waitcnt lgkmcnt(2)
	v_mfma_f32_16x16x4_f32 v[244:247], v94, v110, v[244:247]
	s_waitcnt lgkmcnt(1)
	v_mfma_f32_16x16x4_f32 v[240:243], v95, v111, v[240:243]
	s_nop 9
	v_add_f32_e32 v244, v244, v240
	v_add_f32_e32 v245, v245, v241
	v_add_f32_e32 v246, v246, v242
	v_add_f32_e32 v247, v247, v243
	v_cmp_le_i32_e64 s[96:97], 0, v76
	v_cmp_le_i32_e64 s[100:101], 1, v76
	s_nop 0
	v_cndmask_b32_e64 v128, 0, v244, s[96:97]
	v_cndmask_b32_e64 v129, 0, v245, s[100:101]
	v_cmp_le_i32_e64 s[96:97], 2, v76
	v_cmp_le_i32_e64 s[100:101], 3, v76
	s_nop 0
	v_cndmask_b32_e64 v130, 0, v246, s[96:97]
	v_cndmask_b32_e64 v131, 0, v247, s[100:101]
	s_bfe_u32 s96, s62, 0x20006
	s_and_b32 s97, s96, 1
	s_mul_i32 s97, s97, 0x2700
	s_mov_b32 s101, 0x1c000
	s_mov_b32 s100, 0x6100
	s_bitcmp0_b32 s65, 0
	s_cselect_b32 s101, 0xe000, s101
	s_cselect_b32 s100, 0x4e00, s100
	s_cmp_gt_u32 s96, 1
	s_cselect_b32 s100, s100, 0
	s_add_i32 s97, s97, s101
	s_add_i32 s97, s97, s100
	v_xor_b32_e32 v74, v224, v234
	v_lshl_add_u32 v74, v74, 4, s97
	ds_write_b128 v74, v[128:131] offset:8448
	v_lshlrev_b32_e32 v75, 7, v234
	v_lshl_add_u32 v75, v233, 2, v75
	v_add_u32_e32 v75, s97, v75
	v_cmp_le_i32_e64 s[96:97], 0, v77
	v_cmp_le_i32_e64 s[100:101], 1, v77
	s_nop 0
	v_cndmask_b32_e64 v132, 0, v244, s[96:97]
	v_cndmask_b32_e64 v133, 0, v245, s[100:101]
	v_cmp_le_i32_e64 s[96:97], 2, v77
	v_cmp_le_i32_e64 s[100:101], 3, v77
	s_nop 0
	v_cndmask_b32_e64 v134, 0, v246, s[96:97]
	v_cndmask_b32_e64 v135, 0, v247, s[100:101]
	s_mov_b64 exec, 0x00ff00ff
	ds_write_b32 v75, v132 offset:9472
	ds_write_b32 v75, v133 offset:9504
	ds_write_b32 v75, v134 offset:9536
	ds_write_b32 v75, v135 offset:9568
	s_mov_b64 exec, -1
	s_setprio 0
	s_branch .LBB0_655
	s_nop 0
	s_nop 0
	s_nop 0
	s_nop 0
	s_nop 0
	s_nop 0
	s_nop 0
	s_nop 0
	s_nop 0
	s_nop 0
	s_nop 0
	s_nop 0
	s_nop 0
	s_nop 0
	s_nop 0
	s_nop 0
	s_nop 0
	s_nop 0
	s_nop 0
	s_nop 0
	s_nop 0
	s_nop 0
	s_nop 0
	s_nop 0
	s_nop 0
	s_nop 0
	s_nop 0
	s_nop 0
	s_nop 0
	s_nop 0
	s_nop 0
	s_nop 0
	s_nop 0
	s_nop 0
	s_nop 0
	s_nop 0
	s_nop 0
	s_nop 0
	s_nop 0
	s_nop 0
	s_nop 0
	s_nop 0
